# attention output: 4 dwordx2 stores per lane and pass widened to 2 dwordx4 via v_permlane16_swap
# baseline (speedup 1.0000x reference)
; __device__ __forceinline__ void attn_item(const Args& a, LAS unsigned char* lds, int item, int tid, int wave, int lane) {
;     ...
;     const int fr = lane & 15, fq = lane >> 4;
;     const size_t rowbase = (size_t)b * SEQ;
;     const int grp = tid & 3;
;     u32x4 kk[2][2], vv[2][2], qq[2][2]; f32x4 tk[2][4], tq[2][4];
;     ...
;         bf16_t* op = HO + (rowbase + q0 + 16 * rt + fr) * DM + 512 + (kvh * 4 + g) * 64 + 4 * fq;
.Lsp_post_end:
	s_or_b64 exec, exec, s[4:5]
	v_lshrrev_b32_e32 v254, 4, v152
	v_and_b32_e32 v254, 1, v254
	v_mul_u32_u24_e32 v254, 24, v254
	v_mov_b32_e32 v255, 0
	s_movk_i32 s1, 0x300
	v_cmp_gt_u32_e64 s[4:5], s1, v153
	v_add_u32_e32 v6, 0x200, v153
	s_movk_i32 s1, 0x100
	v_and_b32_e32 v1, 3, v153
	v_lshrrev_b32_e32 v3, 2, v153
	v_mov_b32_e32 v5, 0xbf
	v_lshrrev_b32_e32 v6, 2, v6
	v_cmp_gt_u32_e64 s[6:7], s1, v153
	v_cndmask_b32_e64 v93, v5, v3, s[4:5]
	s_movk_i32 s12, 0x18e0
	v_cndmask_b32_e64 v95, v5, v6, s[6:7]
	v_lshl_add_u32 v5, v1, 5, 0
	v_lshlrev_b32_e32 v4, 4, v1
	v_cmp_eq_u32_e64 s[8:9], 0, v1
	v_cmp_ne_u32_e64 s[10:11], 0, v1
	v_mad_u32_u24 v1, v1, s12, v5
	v_and_b32_e32 v94, 0xc0, v3
	v_and_b32_e32 v96, 0x1c0, v6
	v_sub_u32_e32 v97, 0x7f, v3
	v_mul_u32_u24_e32 v7, 0x90, v3
	v_lshl_add_u32 v98, v3, 1, v1
	v_mul_u32_u24_e32 v3, 0x90, v6
	v_lshl_add_u32 v99, v6, 1, v1
	v_lshlrev_b32_e32 v6, 2, v12
	s_lshl_b32 s0, s92, 7
	v_lshl_add_u32 v84, v0, 1, 0
	v_add_u32_e32 v101, 0, v0
	v_or_b32_e32 v0, 2, v6
	s_add_u32 s20, s74, 0x3100000
	v_readlane_b32 s12, v245, 10
	v_cmp_gt_u32_e64 s[16:17], v0, v92
	v_or_b32_e32 v0, 3, v6
	s_addc_u32 s21, s75, 0
	v_mov_b32_e32 v2, 0
	s_lshr_b32 s33, s12, 7
	s_lshl_b32 s12, s78, 5
	v_cmp_gt_u32_e64 s[18:19], v0, v92
	v_mbcnt_lo_u32_b32 v0, -1, 0
	v_bfe_u32 v85, v153, 2, 6
	s_mov_b32 s23, 0
	s_movk_i32 s1, 0x90
	s_and_b32 s38, s12, 32
	v_lshl_or_b32 v100, s33, 6, v92
	v_cmp_gt_u32_e64 s[12:13], v6, v92
	v_cmp_lt_u32_e64 s[14:15], v6, v92
	v_mul_u32_u24_e32 v102, 0x190, v92
	v_mul_i32_i24_e32 v103, 0x190, v56
	s_movk_i32 s39, 0x2400
	v_mov_b64_e32 v[86:87], s[68:69]
	v_lshlrev_b32_e32 v88, 1, v4
	v_mov_b32_e32 v89, v2
	s_mov_b64 s[24:25], 0x1000
	s_movk_i32 s40, 0x1000
	s_mov_b64 s[26:27], 0x1100
	v_mov_b32_e32 v104, 0x2400
	s_mov_b32 s41, 0xff800000
	v_lshlrev_b32_e32 v90, 1, v6
	s_mov_b64 s[28:29], 0x19800400
	s_mov_b32 s42, 0x19800000
	v_add_u32_e32 v105, v5, v7
	v_add_u32_e32 v106, v5, v3
	v_mbcnt_hi_u32_b32 v107, -1, v0
	v_mov_b32_e32 v108, 0xff800000
	s_mov_b32 s43, 0
	s_branch .LBB0_1088

; __device__ __forceinline__ unsigned cvt_pk_bf16(float lo, float hi) { unsigned r; asm volatile("v_cvt_pk_bf16_f32 %0, %1, %2" : "=v"(r) : "v"(lo), "v"(hi)); return r; }
; __device__ __forceinline__ void attn_item(const Args& a, LAS unsigned char* lds, int item, int tid, int wave, int lane) {
;     ...
; #pragma unroll
;         for (int i = 0; i < 4; ++i) { if (!(4 * fq + i > fr)) s[0][i] = -INFINITY; if (!(4 * fq + i <= fr)) s[8][i] = -INFINITY; }
;         if (q0 < 128) {
; #pragma unroll
;             for (int t = 0; t < 9; ++t)
; #pragma unroll
;                 for (int i = 0; i < 4; ++i) { if (q0 - 128 + 16 * (rt + t) + 4 * fq + i < 0) s[t][i] = -INFINITY; }
;         }
;         float mx = sink;
; #pragma unroll
;         for (int t = 0; t < 9; ++t) mx = fmaxf(mx, fmaxf(fmaxf(s[t][0], s[t][1]), fmaxf(s[t][2], s[t][3])));
;         mx = fmaxf(mx, __shfl_xor(mx, 16)); mx = fmaxf(mx, __shfl_xor(mx, 32));
;         const float nmx2 = -mx * LOG2E;
;         float sum = 0.f;
; #pragma unroll
;         for (int t = 0; t < 9; ++t)
; #pragma unroll
;             for (int i = 0; i < 4; ++i) { const float p = __builtin_amdgcn_exp2f(__builtin_fmaf(s[t][i], LOG2E, nmx2)); s[t][i] = p; sum += p; }
;         sum += __shfl_xor(sum, 16); sum += __shfl_xor(sum, 32);
;         const float inv = __builtin_amdgcn_rcpf(sum + __builtin_amdgcn_exp2f(__builtin_fmaf(sink, LOG2E, nmx2)));
;         bf16x8 pf[5];
; #pragma unroll
;         for (int ks = 0; ks < 5; ++ks) {
;             u32x4 w; w.x = cvt_pk_bf16(s[2 * ks][0], s[2 * ks][1]); w.y = cvt_pk_bf16(s[2 * ks][2], s[2 * ks][3]);
;             if (ks < 4) { w.z = cvt_pk_bf16(s[2 * ks + 1][0], s[2 * ks + 1][1]); w.w = cvt_pk_bf16(s[2 * ks + 1][2], s[2 * ks + 1][3]); } else { w.z = 0u; w.w = 0u; }
;             pf[ks] = __builtin_bit_cast(bf16x8, w);
.LBB0_1102:
	v_lshl_add_u32 v246, s45, 1, v101
	v_add_u32_e32 v247, v246, v102
	v_add_u32_e32 v248, v246, v103
	v_add_u32_e32 v249, 0x6800, v247
	v_add_u32_e32 v250, 0x8000, v247
	v_add_u32_e32 v251, 0x100, v247
	v_add_u32_e32 v252, 0x9800, v247
	v_add_u32_e32 v253, 0x6800, v248
	ds_read2_b64 v[160:163], v249 offset0:128 offset1:132
	ds_read2_b64 v[164:167], v249 offset0:136 offset1:140
	ds_read2_b64 v[168:171], v249 offset0:144 offset1:148
	ds_read2_b64 v[172:175], v249 offset0:152 offset1:156
	ds_read2st64_b64 v[176:179], v251 offset0:54 offset1:66
	ds_read2_b64 v[180:183], v250 offset0:164 offset1:168
	ds_read2_b64 v[184:187], v250 offset0:172 offset1:176
	ds_read2_b64 v[188:191], v250 offset0:180 offset1:184
	ds_read2_b64 v[192:195], v250 offset0:188 offset1:192
	ds_read2_b64 v[200:203], v252 offset0:192 offset1:196
	ds_read2_b64 v[204:207], v252 offset0:200 offset1:204
	ds_read2_b64 v[208:211], v252 offset0:208 offset1:212
	v_mov_b32_e32 v196, 0
	v_mov_b32_e32 v197, 0
	v_mov_b32_e32 v218, 0
	v_mov_b32_e32 v219, 0
	v_mov_b32_e32 v238, 0
	v_mov_b32_e32 v239, 0
	v_mov_b32_e32 v242, 0
	v_mov_b32_e32 v243, 0
	v_mov_b32_e32 v38, s41
	v_cndmask_b32_e64 v37, v32, v38, s[12:13]
	v_cndmask_b32_e64 v32, v37, v32, s[14:15]
	v_max_f32_e32 v37, v36, v36
	v_max_f32_e32 v38, v0, v0
	v_max_f32_e32 v37, v38, v37
	v_max_f32_e32 v38, v1, v1
	v_max_f32_e32 v39, v3, v3
	v_max_f32_e32 v38, v39, v38
	v_max3_f32 v37, v40, v37, v38
	v_max_f32_e32 v38, v31, v31
	v_max_f32_e32 v39, v30, v30
	v_max_f32_e32 v38, v39, v38
	v_max_f32_e32 v39, v27, v27
	v_max_f32_e32 v44, v26, v26
	v_max_f32_e32 v39, v44, v39
	v_max3_f32 v38, v28, v29, v38
	v_max3_f32 v39, v24, v25, v39
	v_max3_f32 v37, v37, v38, v39
	v_max_f32_e32 v38, v23, v23
	v_max_f32_e32 v39, v22, v22
	v_max_f32_e32 v38, v39, v38
	v_max_f32_e32 v39, v19, v19
	v_max_f32_e32 v44, v18, v18
	v_max_f32_e32 v39, v44, v39
	v_max3_f32 v38, v20, v21, v38
	v_max3_f32 v39, v16, v17, v39
	v_max3_f32 v37, v37, v38, v39
	v_max_f32_e32 v38, v15, v15
	v_max_f32_e32 v39, v14, v14
	v_max_f32_e32 v38, v39, v38
	v_max_f32_e32 v39, v11, v11
	v_max_f32_e32 v44, v10, v10
	v_max_f32_e32 v39, v44, v39
	v_max3_f32 v38, v12, v13, v38
	v_max3_f32 v39, v8, v9, v39
	v_cndmask_b32_e64 v34, v34, v108, s[16:17]
	v_cndmask_b32_e64 v35, v35, v108, s[18:19]
	v_max3_f32 v37, v37, v38, v39
	v_max_f32_e32 v38, v7, v7
	v_max_f32_e32 v39, v6, v6
	v_max_f32_e32 v38, v39, v38
	v_max_f32_e32 v39, v35, v35
	v_max_f32_e32 v44, v34, v34
	v_cndmask_b32_e64 v33, v108, v33, s[14:15]
	v_max_f32_e32 v39, v44, v39
	v_max3_f32 v38, v4, v5, v38
	v_max3_f32 v39, v32, v33, v39
	v_max3_f32 v37, v37, v38, v39
	ds_bpermute_b32 v38, v41, v37
	v_lshl_add_u32 v71, s45, 1, v101
	v_add_u32_e32 v72, v71, v102
	v_mov_b32_e32 v91, v2
	s_xor_b64 s[36:37], s[36:37], -1
	s_waitcnt lgkmcnt(0)
	v_max_f32_e32 v38, v38, v38
	v_max_f32_e32 v37, v37, v38
	ds_bpermute_b32 v38, v42, v37
	s_waitcnt lgkmcnt(0)
	ds_read2_b64 v[212:215], v252 offset0:216 offset1:220
	ds_read_b64 v[216:217], v247 offset:40704
	ds_read2_b64 v[220:223], v253 offset0:128 offset1:132
	ds_read2_b64 v[224:227], v253 offset0:136 offset1:140
	ds_read2_b64 v[228:231], v253 offset0:144 offset1:148
	ds_read2_b64 v[232:235], v253 offset0:152 offset1:156
	ds_read_b64 v[240:241], v248 offset:27904
	v_max_f32_e32 v38, v38, v38
	v_max_f32_e32 v37, v37, v38
	v_mul_f32_e32 v50, 0xbfb8aa3b, v37
	v_fmamk_f32 v4, v4, 0x3fb8aa3b, v50
	v_fmamk_f32 v0, v0, 0x3fb8aa3b, v50
	v_exp_f32_e32 v63, v4
	v_fmamk_f32 v4, v5, 0x3fb8aa3b, v50
	v_exp_f32_e32 v0, v0
	v_fmamk_f32 v36, v36, 0x3fb8aa3b, v50
	v_exp_f32_e32 v64, v4
	v_fmamk_f32 v4, v6, 0x3fb8aa3b, v50
	v_exp_f32_e32 v36, v36
	v_fmamk_f32 v3, v3, 0x3fb8aa3b, v50
	v_exp_f32_e32 v65, v4
	v_fmamk_f32 v4, v7, 0x3fb8aa3b, v50
	v_exp_f32_e32 v3, v3
	v_fmamk_f32 v1, v1, 0x3fb8aa3b, v50
	v_exp_f32_e32 v66, v4
	v_fmamk_f32 v4, v32, 0x3fb8aa3b, v50
	v_exp_f32_e32 v1, v1
	v_fmamk_f32 v28, v28, 0x3fb8aa3b, v50
	v_fmamk_f32 v24, v24, 0x3fb8aa3b, v50
	v_fmamk_f32 v20, v20, 0x3fb8aa3b, v50
	v_fmamk_f32 v16, v16, 0x3fb8aa3b, v50
	v_fmamk_f32 v12, v12, 0x3fb8aa3b, v50
	v_fmamk_f32 v8, v8, 0x3fb8aa3b, v50
	v_exp_f32_e32 v67, v4
	v_fmamk_f32 v4, v33, 0x3fb8aa3b, v50
	v_add_f32_e32 v37, 0, v0
	v_exp_f32_e32 v28, v28
	v_fmamk_f32 v29, v29, 0x3fb8aa3b, v50
	v_exp_f32_e32 v38, v24
	v_fmamk_f32 v24, v25, 0x3fb8aa3b, v50
	v_exp_f32_e32 v46, v20
	v_fmamk_f32 v20, v21, 0x3fb8aa3b, v50
	v_exp_f32_e32 v51, v16
	v_fmamk_f32 v16, v17, 0x3fb8aa3b, v50
	v_exp_f32_e32 v55, v12
	v_fmamk_f32 v12, v13, 0x3fb8aa3b, v50
	v_exp_f32_e32 v59, v8
	v_fmamk_f32 v8, v9, 0x3fb8aa3b, v50
	v_exp_f32_e32 v68, v4
	v_fmamk_f32 v4, v34, 0x3fb8aa3b, v50
	v_add_f32_e32 v37, v36, v37
	v_exp_f32_e32 v29, v29
	v_fmamk_f32 v30, v30, 0x3fb8aa3b, v50
	v_exp_f32_e32 v39, v24
	v_fmamk_f32 v24, v26, 0x3fb8aa3b, v50
	v_exp_f32_e32 v47, v20
	v_fmamk_f32 v20, v22, 0x3fb8aa3b, v50
	v_exp_f32_e32 v52, v16
	v_fmamk_f32 v16, v18, 0x3fb8aa3b, v50
	v_exp_f32_e32 v56, v12
	v_fmamk_f32 v12, v14, 0x3fb8aa3b, v50
	v_exp_f32_e32 v60, v8
	v_fmamk_f32 v8, v10, 0x3fb8aa3b, v50
	v_exp_f32_e32 v69, v4
	v_fmamk_f32 v4, v35, 0x3fb8aa3b, v50
	v_add_f32_e32 v37, v3, v37
	v_exp_f32_e32 v30, v30
	v_fmamk_f32 v31, v31, 0x3fb8aa3b, v50
	v_exp_f32_e32 v44, v24
	v_fmamk_f32 v24, v27, 0x3fb8aa3b, v50
	v_exp_f32_e32 v48, v20
	v_fmamk_f32 v20, v23, 0x3fb8aa3b, v50
	v_exp_f32_e32 v53, v16
	v_fmamk_f32 v16, v19, 0x3fb8aa3b, v50
	v_exp_f32_e32 v57, v12
	v_fmamk_f32 v12, v15, 0x3fb8aa3b, v50
	v_exp_f32_e32 v61, v8
	v_fmamk_f32 v8, v11, 0x3fb8aa3b, v50
	v_exp_f32_e32 v70, v4
	v_cvt_pk_bf16_f32 v4, v0, v36
	v_cvt_pk_bf16_f32 v5, v3, v1
	v_add_u32_e32 v3, 0x6800, v72
	v_add_f32_e32 v37, v1, v37
	v_exp_f32_e32 v31, v31
	v_exp_f32_e32 v45, v24
	v_exp_f32_e32 v49, v20
	v_exp_f32_e32 v54, v16
	v_exp_f32_e32 v58, v12
	v_exp_f32_e32 v62, v8
	v_cvt_pk_bf16_f32 v6, v28, v29
	v_cvt_pk_bf16_f32 v7, v30, v31
	v_cvt_pk_bf16_f32 v8, v38, v39
	v_cvt_pk_bf16_f32 v9, v44, v45
	v_cvt_pk_bf16_f32 v10, v46, v47
	v_cvt_pk_bf16_f32 v11, v48, v49
	v_cvt_pk_bf16_f32 v12, v51, v52
	v_cvt_pk_bf16_f32 v13, v53, v54
	v_cvt_pk_bf16_f32 v14, v55, v56
	v_cvt_pk_bf16_f32 v15, v57, v58
	v_cvt_pk_bf16_f32 v16, v59, v60
	v_cvt_pk_bf16_f32 v17, v61, v62
	v_cvt_pk_bf16_f32 v18, v63, v64
	v_cvt_pk_bf16_f32 v19, v65, v66
	v_cvt_pk_bf16_f32 v0, v67, v68
	v_cvt_pk_bf16_f32 v1, v69, v70
	v_add_f32_e32 v37, v28, v37
	v_add_f32_e32 v24, v29, v37
	v_add_f32_e32 v24, v30, v24
	v_add_f32_e32 v28, v31, v24
	v_add_f32_e32 v28, v38, v28
	v_add_f32_e32 v28, v39, v28
	v_add_f32_e32 v32, v44, v28
	s_waitcnt lgkmcnt(0)
; #define LAS __attribute__((address_space(3)))
; __device__ __forceinline__ unsigned cvt_pk_bf16(float lo, float hi) { unsigned r; asm volatile("v_cvt_pk_bf16_f32 %0, %1, %2" : "=v"(r) : "v"(lo), "v"(hi)); return r; }
; #define MFMA16(a, b, c) __builtin_amdgcn_mfma_f32_16x16x32_bf16((a), (b), (c), 0, 0, 0)
; __device__ __forceinline__ void attn_item(const Args& a, LAS unsigned char* lds, int item, int tid, int wave, int lane) {
;     ...
;         f32x4 o[4];
; #pragma unroll
;         for (int dt = 0; dt < 4; ++dt) {
;             f32x4 acc = (f32x4){0.f, 0.f, 0.f, 0.f};
;             const LAS bf16_t* vp = VT + (16 * dt + fr) * VP + 16 * rt + 4 * fq;
; #pragma unroll
;             for (int ks = 0; ks < 5; ++ks) {
;                 u32x4 w; const u32x2 lo = *(const LAS u32x2*)(vp + 32 * ks); w.x = lo.x; w.y = lo.y;
;                 if (ks < 4) { const u32x2 hi2 = *(const LAS u32x2*)(vp + 32 * ks + 16); w.z = hi2.x; w.w = hi2.y; } else { w.z = 0u; w.w = 0u; }
;                 acc = MFMA16(__builtin_bit_cast(bf16x8, w), pf[ks], acc);
;             }
;             o[dt] = acc;
;         }
;         bf16_t* op = HO + (rowbase + q0 + 16 * rt + fr) * DM + 512 + (kvh * 4 + g) * 64 + 4 * fq;
; #pragma unroll
;         for (int dt = 0; dt < 4; ++dt) { u32x2 w; w.x = cvt_pk_bf16(o[dt][0] * inv, o[dt][1] * inv); w.y = cvt_pk_bf16(o[dt][2] * inv, o[dt][3] * inv); *(u32x2*)(op + 16 * dt) = w; }
	v_mfma_f32_16x16x32_bf16 v[20:23], v[160:163], v[4:7], 0
	v_add_f32_e32 v32, v45, v32
	v_add_f32_e32 v32, v46, v32
	v_add_f32_e32 v32, v47, v32
	s_waitcnt lgkmcnt(0)
	v_mfma_f32_16x16x32_bf16 v[20:23], v[164:167], v[8:11], v[20:23]
	v_add_f32_e32 v3, v48, v32
	v_add_u32_e32 v44, 0x8000, v72
	s_waitcnt lgkmcnt(0)
	v_mfma_f32_16x16x32_bf16 v[20:23], v[168:171], v[12:15], v[20:23]
	v_add_u32_e32 v28, 0x100, v72
	v_add_f32_e32 v3, v49, v3
	s_waitcnt lgkmcnt(0)
	v_mfma_f32_16x16x32_bf16 v[20:23], v[172:175], v[16:19], v[20:23]
	s_waitcnt lgkmcnt(0)
	v_add_f32_e32 v3, v51, v3
	v_add_f32_e32 v36, v52, v3
	v_mov_b32_e32 v3, v2
	v_mov_b32_e32 v236, v176
	v_mov_b32_e32 v237, v177
	s_nop 1
	v_mfma_f32_16x16x32_bf16 v[20:23], v[236:239], v[0:3], v[20:23]
	v_add_f32_e32 v24, v53, v36
	v_add_f32_e32 v45, v54, v24
	s_waitcnt lgkmcnt(0)
	s_waitcnt lgkmcnt(0)
	v_mfma_f32_16x16x32_bf16 v[28:31], v[178:181], v[4:7], 0
	s_waitcnt lgkmcnt(0)
	v_mfma_f32_16x16x32_bf16 v[28:31], v[182:185], v[8:11], v[28:31]
	v_add_f32_e32 v36, v55, v45
	v_add_u32_e32 v45, 0x9800, v72
	v_mfma_f32_16x16x32_bf16 v[24:27], v[186:189], v[12:15], v[28:31]
	v_add_f32_e32 v44, v56, v36
	v_add_u32_e32 v49, v71, v103
	v_add_u32_e32 v51, 0x6800, v49
	s_nop 0
	s_waitcnt lgkmcnt(0)
	v_mfma_f32_16x16x32_bf16 v[24:27], v[190:193], v[16:19], v[24:27]
	v_add_f32_e32 v28, v57, v44
	v_add_f32_e32 v44, v58, v28
	v_mfma_f32_16x16x32_bf16 v[24:27], v[194:197], v[0:3], v[24:27]
	v_add_f32_e32 v32, v59, v44
	v_add_f32_e32 v44, v60, v32
	s_waitcnt lgkmcnt(0)
	v_mfma_f32_16x16x32_bf16 v[36:39], v[200:203], v[4:7], 0
	v_add_f32_e32 v44, v61, v44
	v_add_f32_e32 v44, v62, v44
	v_add_f32_e32 v44, v63, v44
	s_waitcnt lgkmcnt(0)
	v_mfma_f32_16x16x32_bf16 v[28:31], v[204:207], v[8:11], v[36:39]
	v_add_f32_e32 v44, v64, v44
	v_add_f32_e32 v48, v65, v44
	v_add_f32_e32 v52, v66, v48
	s_waitcnt lgkmcnt(0)
	v_mfma_f32_16x16x32_bf16 v[28:31], v[208:211], v[12:15], v[28:31]
	s_waitcnt lgkmcnt(0)
	v_mfma_f32_16x16x32_bf16 v[28:31], v[212:215], v[16:19], v[28:31]
	v_fmac_f32_e32 v50, 0x3fb8aa3b, v40
	s_waitcnt lgkmcnt(0)
	v_mfma_f32_16x16x32_bf16 v[28:31], v[216:219], v[0:3], v[28:31]
	v_add_f32_e32 v32, v67, v52
	v_add_f32_e32 v32, v68, v32
	v_add_f32_e32 v52, v69, v32
	s_waitcnt lgkmcnt(0)
	v_mfma_f32_16x16x32_bf16 v[4:7], v[220:223], v[4:7], 0
	v_add_f32_e32 v44, v70, v52
	ds_bpermute_b32 v45, v41, v44
	s_waitcnt lgkmcnt(0)
	v_mfma_f32_16x16x32_bf16 v[4:7], v[224:227], v[8:11], v[4:7]
	v_mov_b32_e32 v51, v2
	s_waitcnt lgkmcnt(0)
	v_add_f32_e32 v36, v44, v45
	v_mfma_f32_16x16x32_bf16 v[4:7], v[228:231], v[12:15], v[4:7]
	ds_bpermute_b32 v12, v42, v36
	v_exp_f32_e32 v13, v50
	v_mov_b32_e32 v50, v2
	s_waitcnt lgkmcnt(0)
	v_mfma_f32_16x16x32_bf16 v[4:7], v[232:235], v[16:19], v[4:7]
	s_waitcnt lgkmcnt(0)
	v_add_f32_e32 v8, v36, v12
	v_add_f32_e32 v8, v13, v8
	v_mfma_f32_16x16x32_bf16 v[4:7], v[240:243], v[0:3], v[4:7]
	v_or_b32_e32 v0, s45, v43
	v_or_b32_e32 v0, s30, v0
	v_mov_b32_e32 v1, s31
	v_rcp_f32_e32 v3, v8
	v_lshlrev_b64 v[0:1], 11, v[0:1]
	v_lshl_add_u64 v[0:1], s[74:75], 0, v[0:1]
	v_lshl_add_u64 v[0:1], v[0:1], 0, s[22:23]
	v_lshl_add_u64 v[0:1], v[0:1], 0, v[90:91]
	v_lshl_add_u64 v[8:9], v[0:1], 0, s[28:29]
	v_lshl_add_u64 v[8:9], v[8:9], 0, v[254:255]
	v_mul_f32_e32 v10, v20, v3
	v_mul_f32_e32 v11, v21, v3
	v_cvt_pk_bf16_f32 v160, v10, v11
	v_mul_f32_e32 v10, v22, v3
	v_mul_f32_e32 v11, v23, v3
	v_cvt_pk_bf16_f32 v161, v10, v11
	v_mul_f32_e32 v10, v24, v3
	v_mul_f32_e32 v11, v25, v3
	v_cvt_pk_bf16_f32 v162, v10, v11
	v_mul_f32_e32 v10, v26, v3
	v_mul_f32_e32 v11, v27, v3
	v_cvt_pk_bf16_f32 v163, v10, v11
	v_mul_f32_e32 v10, v28, v3
	v_mul_f32_e32 v11, v29, v3
	v_cvt_pk_bf16_f32 v164, v10, v11
	v_mul_f32_e32 v10, v30, v3
	v_mul_f32_e32 v11, v31, v3
	v_cvt_pk_bf16_f32 v165, v10, v11
	v_mul_f32_e32 v10, v4, v3
	v_mul_f32_e32 v11, v5, v3
	v_cvt_pk_bf16_f32 v166, v10, v11
	v_mul_f32_e32 v10, v6, v3
	v_mul_f32_e32 v11, v7, v3
	v_cvt_pk_bf16_f32 v167, v10, v11
	s_mov_b32 s45, 16
	s_andn2_b64 vcc, exec, s[36:37]
	s_mov_b64 s[36:37], 0
	s_nop 1
	v_permlane16_swap_b32_e32 v160, v162
	v_permlane16_swap_b32_e32 v161, v163
	v_permlane16_swap_b32_e32 v164, v166
	v_permlane16_swap_b32_e32 v165, v167
	global_store_dwordx4 v[8:9], v[160:163], off
	global_store_dwordx4 v[8:9], v[164:167], off offset:64
	s_cbranch_vccz .LBB0_1087
